# norm phase: hand-written fast path (all row loads issued up front, DPP/permlane reductions); adaLN deterministic rewrite
# speedup vs baseline: 1.0031x; 1.0026x over previous
.LBB0_899:
	s_andn2_b64 vcc, exec, s[68:69]
	s_cbranch_vccnz .LBB0_1130
	v_readlane_b32 s0, v255, 11
	s_cmp_gt_i32 s0, 0
	s_mov_b64 s[2:3], -1
	s_cbranch_scc0 .LBB0_1013
	s_mov_b32 s0, s67
	s_mov_b32 s79, s0
	s_lshl_b32 s1, s0, 3
	v_readlane_b32 s0, v254, 63
	v_writelane_b32 v255, s58, 22
	s_add_i32 s1, s1, s0
	s_mov_b32 s67, 0x7f800000
	v_writelane_b32 v255, s59, 23
	v_mov_b32_e32 v0, v1
	s_cmpk_gt_i32 s1, 0x7ff
	s_cbranch_scc1 .LBB0_1012
	s_mov_b32 s100, s80
	s_ashr_i32 s0, s80, 2
	s_and_b32 s8, s80, 3
	s_cmp_eq_u32 s80, 1
	v_readlane_b32 s10, v255, 14
	s_cselect_b64 s[56:57], -1, 0
	s_or_b32 s2, s8, s0
	v_readlane_b32 s11, v255, 15
	s_cmp_lg_u32 s2, 0
	s_load_dwordx2 s[2:3], s[10:11], 0x58
	s_mul_i32 s0, s0, 3
	s_cselect_b64 s[94:95], -1, 0
	s_add_i32 s6, s0, s8
	s_ashr_i32 s7, s6, 31
	s_lshl_b64 s[6:7], s[6:7], 12
	s_waitcnt lgkmcnt(0)
	s_add_u32 s2, s2, s6
	s_addc_u32 s3, s3, s7
	v_mbcnt_lo_u32_b32 v0, -1, v0
	s_add_u32 s70, s10, 8
	v_mbcnt_hi_u32_b32 v92, -1, v0
	s_addc_u32 s71, s11, 0
	s_mulk_i32 s8, 0x3000
	v_readlane_b32 s6, v255, 22
	s_mul_i32 s80, s1, 6
	v_lshlrev_b32_e32 v94, 3, v92
	s_add_u32 s1, s6, s8
	v_ashrrev_i32_e32 v93, 31, v92
	v_readlane_b32 s8, v255, 5
	v_ashrrev_i32_e32 v95, 31, v94
	s_waitcnt vmcnt(0)
	v_lshlrev_b64 v[4:5], 2, v[92:93]
	v_readlane_b32 s10, v255, 7
	v_readlane_b32 s11, v255, 8
	v_lshl_add_u64 v[100:101], v[94:95], 2, s[2:3]
	v_lshlrev_b64 v[102:103], 5, v[94:95]
	v_lshl_add_u64 v[6:7], s[10:11], 0, v[4:5]
	s_mov_b64 s[10:11], 0x200000
	s_mov_b64 s[2:3], 0x4000
	v_readlane_b32 s7, v255, 23
	v_lshl_add_u64 v[98:99], v[6:7], 0, s[10:11]
	v_or_b32_e32 v6, 4, v94
	v_lshl_add_u64 v[104:105], v[102:103], 0, s[2:3]
	s_mov_b64 s[2:3], 0x4040
	s_addc_u32 s54, s7, 0
	v_ashrrev_i32_e32 v7, 31, v6
	v_lshl_add_u64 v[114:115], v[102:103], 0, s[2:3]
	s_mov_b64 s[2:3], 0x40c0
	s_ashr_i32 s81, s80, 31
	v_readlane_b32 s6, v255, 9
	v_lshlrev_b32_e32 v0, 2, v92
	v_add_u32_e32 v106, 0x204, v94
	v_or_b32_e32 v8, 2, v94
	v_lshlrev_b64 v[110:111], 5, v[6:7]
	v_or_b32_e32 v6, 6, v94
	v_lshl_add_u64 v[118:119], v[102:103], 0, s[2:3]
	s_lshl_b64 s[2:3], s[80:81], 6
	v_lshlrev_b64 v[2:3], 1, v[94:95]
	v_readlane_b32 s7, v255, 10
	v_xor_b32_e32 v126, 4, v0
	v_xor_b32_e32 v127, 8, v0
	v_xor_b32_e32 v128, 16, v0
	v_xor_b32_e32 v129, 32, v0
	v_xor_b32_e32 v130, 64, v0
	v_xor_b32_e32 v131, 0x80, v0
	v_and_b32_e32 v0, 4, v92
	v_ashrrev_i32_e32 v107, 31, v106
	v_ashrrev_i32_e32 v9, 31, v8
	v_ashrrev_i32_e32 v7, 31, v6
	v_lshl_add_u64 v[120:121], s[2:3], 0, v[4:5]
	s_lshl_b64 s[2:3], s[80:81], 11
	v_lshl_add_u64 v[96:97], s[6:7], 0, v[2:3]
	v_cmp_gt_i32_e64 s[6:7], 16, v92
	v_cmp_ne_u32_e64 s[74:75], 0, v0
	v_lshlrev_b64 v[108:109], 5, v[8:9]
	v_lshlrev_b64 v[112:113], 5, v[6:7]
	v_lshlrev_b64 v[116:117], 5, v[106:107]
	v_cmp_eq_u32_e64 s[68:69], 15, v92
	v_cmp_eq_u32_e64 s[12:13], 14, v92
	v_cmp_eq_u32_e64 s[14:15], 13, v92
	v_cmp_eq_u32_e64 s[16:17], 12, v92
	v_cmp_eq_u32_e64 s[18:19], 11, v92
	v_cmp_eq_u32_e64 s[20:21], 10, v92
	v_cmp_eq_u32_e64 s[22:23], 9, v92
	v_cmp_eq_u32_e64 s[24:25], 8, v92
	v_cmp_eq_u32_e64 s[26:27], 7, v92
	v_cmp_eq_u32_e64 s[28:29], 6, v92
	v_cmp_eq_u32_e64 s[30:31], 5, v92
	v_cmp_eq_u32_e64 s[34:35], 4, v92
	v_cmp_eq_u32_e64 s[36:37], 3, v92
	v_cmp_eq_u32_e64 s[38:39], 2, v92
	v_cmp_eq_u32_e64 s[40:41], 1, v92
	v_cmp_eq_u32_e64 s[42:43], 0, v92
	v_lshl_add_u64 v[122:123], s[2:3], 0, v[2:3]
	v_readlane_b32 s9, v255, 6
	s_and_b64 vcc, exec, s[56:57]
	s_cbranch_vccnz .LBB0_906
	s_sub_i32 s2, s80, 0x1800
	s_max_i32 s2, s2, 0
	s_lshr_b32 s2, s2, 11
	s_sub_i32 s3, s80, 0x17fb
	s_max_i32 s3, s3, 0
	s_lshr_b32 s3, s3, 11
	s_cmp_lg_u32 s2, s3
	s_cbranch_scc1 .LBB0_906
	s_mov_b32 s1, s2
	s_ashr_i32 s3, s100, 2
	s_and_b32 s6, s100, 3
	s_mul_i32 s7, s3, 3
	s_add_i32 s8, s7, s6
	v_readlane_b32 s10, v255, 14
	v_readlane_b32 s11, v255, 15
	s_load_dwordx2 s[12:13], s[10:11], 0x58
	s_load_dwordx4 s[16:19], s[10:11], 0x0
	s_add_i32 s9, s7, s1
	s_mul_i32 s9, s9, 0x9000
	s_mul_i32 s14, s6, 0x3000
	s_add_i32 s9, s9, s14
	s_add_i32 s9, s9, 0x100000
	v_readlane_b32 s20, v255, 7
	v_readlane_b32 s21, v255, 8
	s_add_u32 s20, s20, s9
	s_addc_u32 s21, s21, 0
	v_lshlrev_b32_e32 v82, 5, v92
	v_lshlrev_b32_e32 v83, 4, v92
	s_lshl_b64 s[22:23], s[80:81], 12
	v_readlane_b32 s24, v255, 5
	v_readlane_b32 s25, v255, 6
	s_waitcnt lgkmcnt(0)
	s_and_b64 vcc, exec, s[94:95]
	s_cbranch_vccnz .Lnrm_src
	s_mov_b64 s[24:25], s[16:17]
	s_cmp_eq_u32 s1, 0
	s_cbranch_scc1 .Lnrm_src
	s_add_u32 s24, s18, 0xfe000000
	s_addc_u32 s25, s19, -1
.Lnrm_src:
	s_add_u32 s24, s24, s22
	s_addc_u32 s25, s25, s23
	global_load_dwordx4 v[2:5], v82, s[24:25] offset:0
	global_load_dwordx4 v[6:9], v82, s[24:25] offset:16
	global_load_dwordx4 v[10:13], v82, s[24:25] offset:2048
	global_load_dwordx4 v[14:17], v82, s[24:25] offset:2064
	s_add_u32 s24, s24, 0x1000
	s_addc_u32 s25, s25, 0
	global_load_dwordx4 v[18:21], v82, s[24:25] offset:0
	global_load_dwordx4 v[22:25], v82, s[24:25] offset:16
	global_load_dwordx4 v[26:29], v82, s[24:25] offset:2048
	global_load_dwordx4 v[30:33], v82, s[24:25] offset:2064
	s_add_u32 s24, s24, 0x1000
	s_addc_u32 s25, s25, 0
	global_load_dwordx4 v[34:37], v82, s[24:25] offset:0
	global_load_dwordx4 v[38:41], v82, s[24:25] offset:16
	global_load_dwordx4 v[42:45], v82, s[24:25] offset:2048
	global_load_dwordx4 v[46:49], v82, s[24:25] offset:2064
	s_add_u32 s24, s24, 0x1000
	s_addc_u32 s25, s25, 0
	global_load_dwordx4 v[50:53], v82, s[24:25] offset:0
	global_load_dwordx4 v[54:57], v82, s[24:25] offset:16
	global_load_dwordx4 v[58:61], v82, s[24:25] offset:2048
	global_load_dwordx4 v[62:65], v82, s[24:25] offset:2064
	s_add_u32 s24, s24, 0x1000
	s_addc_u32 s25, s25, 0
	global_load_dwordx4 v[66:69], v82, s[24:25] offset:0
	global_load_dwordx4 v[70:73], v82, s[24:25] offset:16
	global_load_dwordx4 v[74:77], v82, s[24:25] offset:2048
	global_load_dwordx4 v[78:81], v82, s[24:25] offset:2064
	s_add_u32 s24, s24, 0x1000
	s_addc_u32 s25, s25, 0
	global_load_dwordx4 v[132:135], v82, s[24:25] offset:0
	global_load_dwordx4 v[136:139], v82, s[24:25] offset:16
	global_load_dwordx4 v[140:143], v82, s[24:25] offset:2048
	global_load_dwordx4 v[144:147], v82, s[24:25] offset:2064
	s_lshl_b32 s8, s8, 12
	s_add_u32 s12, s12, s8
	s_addc_u32 s13, s13, 0
	s_add_u32 s26, s20, 0x1000
	s_addc_u32 s27, s21, 0
	global_load_dwordx4 v[148:151], v82, s[12:13] offset:0
	global_load_dwordx4 v[170:173], v82, s[26:27] offset:0
	global_load_dwordx4 v[186:189], v82, s[20:21] offset:0
	global_load_dwordx4 v[152:155], v82, s[12:13] offset:16
	global_load_dwordx4 v[174:177], v82, s[26:27] offset:16
	global_load_dwordx4 v[190:193], v82, s[20:21] offset:16
	global_load_dwordx4 v[156:159], v82, s[12:13] offset:2048
	global_load_dwordx4 v[178:181], v82, s[26:27] offset:2048
	global_load_dwordx4 v[194:197], v82, s[20:21] offset:2048
	global_load_dwordx4 v[160:163], v82, s[12:13] offset:2064
	global_load_dwordx4 v[182:185], v82, s[26:27] offset:2064
	global_load_dwordx4 v[198:201], v82, s[20:21] offset:2064
	s_mov_b32 s28, 0x3a800000
	s_waitcnt vmcnt(32)
	v_mul_f32_e32 v202, v2, v2
	v_fmac_f32_e32 v202, v3, v3
	v_fmac_f32_e32 v202, v4, v4
	v_fmac_f32_e32 v202, v5, v5
	v_fmac_f32_e32 v202, v6, v6
	v_fmac_f32_e32 v202, v7, v7
	v_fmac_f32_e32 v202, v8, v8
	v_fmac_f32_e32 v202, v9, v9
	v_fmac_f32_e32 v202, v10, v10
	v_fmac_f32_e32 v202, v11, v11
	v_fmac_f32_e32 v202, v12, v12
	v_fmac_f32_e32 v202, v13, v13
	v_fmac_f32_e32 v202, v14, v14
	v_fmac_f32_e32 v202, v15, v15
	v_fmac_f32_e32 v202, v16, v16
	v_fmac_f32_e32 v202, v17, v17
	s_waitcnt vmcnt(28)
	v_mul_f32_e32 v203, v18, v18
	v_fmac_f32_e32 v203, v19, v19
	v_fmac_f32_e32 v203, v20, v20
	v_fmac_f32_e32 v203, v21, v21
	v_fmac_f32_e32 v203, v22, v22
	v_fmac_f32_e32 v203, v23, v23
	v_fmac_f32_e32 v203, v24, v24
	v_fmac_f32_e32 v203, v25, v25
	v_fmac_f32_e32 v203, v26, v26
	v_fmac_f32_e32 v203, v27, v27
	v_fmac_f32_e32 v203, v28, v28
	v_fmac_f32_e32 v203, v29, v29
	v_fmac_f32_e32 v203, v30, v30
	v_fmac_f32_e32 v203, v31, v31
	v_fmac_f32_e32 v203, v32, v32
	v_fmac_f32_e32 v203, v33, v33
	s_waitcnt vmcnt(24)
	v_mul_f32_e32 v204, v34, v34
	v_fmac_f32_e32 v204, v35, v35
	v_fmac_f32_e32 v204, v36, v36
	v_fmac_f32_e32 v204, v37, v37
	v_fmac_f32_e32 v204, v38, v38
	v_fmac_f32_e32 v204, v39, v39
	v_fmac_f32_e32 v204, v40, v40
	v_fmac_f32_e32 v204, v41, v41
	v_fmac_f32_e32 v204, v42, v42
	v_fmac_f32_e32 v204, v43, v43
	v_fmac_f32_e32 v204, v44, v44
	v_fmac_f32_e32 v204, v45, v45
	v_fmac_f32_e32 v204, v46, v46
	v_fmac_f32_e32 v204, v47, v47
	v_fmac_f32_e32 v204, v48, v48
	v_fmac_f32_e32 v204, v49, v49
	s_waitcnt vmcnt(20)
	v_mul_f32_e32 v205, v50, v50
	v_fmac_f32_e32 v205, v51, v51
	v_fmac_f32_e32 v205, v52, v52
	v_fmac_f32_e32 v205, v53, v53
	v_fmac_f32_e32 v205, v54, v54
	v_fmac_f32_e32 v205, v55, v55
	v_fmac_f32_e32 v205, v56, v56
	v_fmac_f32_e32 v205, v57, v57
	v_fmac_f32_e32 v205, v58, v58
	v_fmac_f32_e32 v205, v59, v59
	v_fmac_f32_e32 v205, v60, v60
	v_fmac_f32_e32 v205, v61, v61
	v_fmac_f32_e32 v205, v62, v62
	v_fmac_f32_e32 v205, v63, v63
	v_fmac_f32_e32 v205, v64, v64
	v_fmac_f32_e32 v205, v65, v65
	s_waitcnt vmcnt(16)
	v_mul_f32_e32 v206, v66, v66
	v_fmac_f32_e32 v206, v67, v67
	v_fmac_f32_e32 v206, v68, v68
	v_fmac_f32_e32 v206, v69, v69
	v_fmac_f32_e32 v206, v70, v70
	v_fmac_f32_e32 v206, v71, v71
	v_fmac_f32_e32 v206, v72, v72
	v_fmac_f32_e32 v206, v73, v73
	v_fmac_f32_e32 v206, v74, v74
	v_fmac_f32_e32 v206, v75, v75
	v_fmac_f32_e32 v206, v76, v76
	v_fmac_f32_e32 v206, v77, v77
	v_fmac_f32_e32 v206, v78, v78
	v_fmac_f32_e32 v206, v79, v79
	v_fmac_f32_e32 v206, v80, v80
	v_fmac_f32_e32 v206, v81, v81
	s_waitcnt vmcnt(12)
	v_mul_f32_e32 v207, v132, v132
	v_fmac_f32_e32 v207, v133, v133
	v_fmac_f32_e32 v207, v134, v134
	v_fmac_f32_e32 v207, v135, v135
	v_fmac_f32_e32 v207, v136, v136
	v_fmac_f32_e32 v207, v137, v137
	v_fmac_f32_e32 v207, v138, v138
	v_fmac_f32_e32 v207, v139, v139
	v_fmac_f32_e32 v207, v140, v140
	v_fmac_f32_e32 v207, v141, v141
	v_fmac_f32_e32 v207, v142, v142
	v_fmac_f32_e32 v207, v143, v143
	v_fmac_f32_e32 v207, v144, v144
	v_fmac_f32_e32 v207, v145, v145
	v_fmac_f32_e32 v207, v146, v146
	v_fmac_f32_e32 v207, v147, v147
	s_nop 1
	v_add_f32_dpp v202, v202, v202 row_ror:8 row_mask:0xf bank_mask:0xf
	v_add_f32_dpp v203, v203, v203 row_ror:8 row_mask:0xf bank_mask:0xf
	v_add_f32_dpp v204, v204, v204 row_ror:8 row_mask:0xf bank_mask:0xf
	v_add_f32_dpp v205, v205, v205 row_ror:8 row_mask:0xf bank_mask:0xf
	v_add_f32_dpp v206, v206, v206 row_ror:8 row_mask:0xf bank_mask:0xf
	v_add_f32_dpp v207, v207, v207 row_ror:8 row_mask:0xf bank_mask:0xf
	v_add_f32_dpp v202, v202, v202 row_ror:4 row_mask:0xf bank_mask:0xf
	v_add_f32_dpp v203, v203, v203 row_ror:4 row_mask:0xf bank_mask:0xf
	v_add_f32_dpp v204, v204, v204 row_ror:4 row_mask:0xf bank_mask:0xf
	v_add_f32_dpp v205, v205, v205 row_ror:4 row_mask:0xf bank_mask:0xf
	v_add_f32_dpp v206, v206, v206 row_ror:4 row_mask:0xf bank_mask:0xf
	v_add_f32_dpp v207, v207, v207 row_ror:4 row_mask:0xf bank_mask:0xf
	v_add_f32_dpp v202, v202, v202 row_ror:2 row_mask:0xf bank_mask:0xf
	v_add_f32_dpp v203, v203, v203 row_ror:2 row_mask:0xf bank_mask:0xf
	v_add_f32_dpp v204, v204, v204 row_ror:2 row_mask:0xf bank_mask:0xf
	v_add_f32_dpp v205, v205, v205 row_ror:2 row_mask:0xf bank_mask:0xf
	v_add_f32_dpp v206, v206, v206 row_ror:2 row_mask:0xf bank_mask:0xf
	v_add_f32_dpp v207, v207, v207 row_ror:2 row_mask:0xf bank_mask:0xf
	v_add_f32_dpp v202, v202, v202 row_ror:1 row_mask:0xf bank_mask:0xf
	v_add_f32_dpp v203, v203, v203 row_ror:1 row_mask:0xf bank_mask:0xf
	v_add_f32_dpp v204, v204, v204 row_ror:1 row_mask:0xf bank_mask:0xf
	v_add_f32_dpp v205, v205, v205 row_ror:1 row_mask:0xf bank_mask:0xf
	v_add_f32_dpp v206, v206, v206 row_ror:1 row_mask:0xf bank_mask:0xf
	v_add_f32_dpp v207, v207, v207 row_ror:1 row_mask:0xf bank_mask:0xf
	v_mov_b32_e32 v208, v202
	v_mov_b32_e32 v209, v203
	v_mov_b32_e32 v210, v204
	v_mov_b32_e32 v211, v205
	v_mov_b32_e32 v212, v206
	v_mov_b32_e32 v213, v207
	s_nop 1
	v_permlane16_swap_b32_e32 v208, v202
	v_permlane16_swap_b32_e32 v209, v203
	v_permlane16_swap_b32_e32 v210, v204
	v_permlane16_swap_b32_e32 v211, v205
	v_permlane16_swap_b32_e32 v212, v206
	v_permlane16_swap_b32_e32 v213, v207
	v_add_f32_e32 v202, v202, v208
	v_add_f32_e32 v203, v203, v209
	v_add_f32_e32 v204, v204, v210
	v_add_f32_e32 v205, v205, v211
	v_add_f32_e32 v206, v206, v212
	v_add_f32_e32 v207, v207, v213
	v_mov_b32_e32 v208, v202
	v_mov_b32_e32 v209, v203
	v_mov_b32_e32 v210, v204
	v_mov_b32_e32 v211, v205
	v_mov_b32_e32 v212, v206
	v_mov_b32_e32 v213, v207
	s_nop 1
	v_permlane32_swap_b32_e32 v208, v202
	v_permlane32_swap_b32_e32 v209, v203
	v_permlane32_swap_b32_e32 v210, v204
	v_permlane32_swap_b32_e32 v211, v205
	v_permlane32_swap_b32_e32 v212, v206
	v_permlane32_swap_b32_e32 v213, v207
	v_add_f32_e32 v202, v202, v208
	v_add_f32_e32 v203, v203, v209
	v_add_f32_e32 v204, v204, v210
	v_add_f32_e32 v205, v205, v211
	v_add_f32_e32 v206, v206, v212
	v_add_f32_e32 v207, v207, v213
	v_fma_f32 v202, v202, s28, v167
	v_fma_f32 v203, v203, s28, v167
	v_fma_f32 v204, v204, s28, v167
	v_fma_f32 v205, v205, s28, v167
	v_fma_f32 v206, v206, s28, v167
	v_fma_f32 v207, v207, s28, v167
	v_rsq_f32_e32 v202, v202
	v_rsq_f32_e32 v203, v203
	v_rsq_f32_e32 v204, v204
	v_rsq_f32_e32 v205, v205
	v_rsq_f32_e32 v206, v206
	v_rsq_f32_e32 v207, v207
	s_waitcnt vmcnt(0)
	v_add_f32_e32 v170, 1.0, v170
	v_add_f32_e32 v171, 1.0, v171
	v_add_f32_e32 v172, 1.0, v172
	v_add_f32_e32 v173, 1.0, v173
	v_add_f32_e32 v174, 1.0, v174
	v_add_f32_e32 v175, 1.0, v175
	v_add_f32_e32 v176, 1.0, v176
	v_add_f32_e32 v177, 1.0, v177
	v_add_f32_e32 v178, 1.0, v178
	v_add_f32_e32 v179, 1.0, v179
	v_add_f32_e32 v180, 1.0, v180
	v_add_f32_e32 v181, 1.0, v181
	v_add_f32_e32 v182, 1.0, v182
	v_add_f32_e32 v183, 1.0, v183
	v_add_f32_e32 v184, 1.0, v184
	v_add_f32_e32 v185, 1.0, v185
	v_mul_f32_e32 v170, v148, v170
	v_mul_f32_e32 v171, v149, v171
	v_mul_f32_e32 v172, v150, v172
	v_mul_f32_e32 v173, v151, v173
	v_mul_f32_e32 v174, v152, v174
	v_mul_f32_e32 v175, v153, v175
	v_mul_f32_e32 v176, v154, v176
	v_mul_f32_e32 v177, v155, v177
	v_mul_f32_e32 v178, v156, v178
	v_mul_f32_e32 v179, v157, v179
	v_mul_f32_e32 v180, v158, v180
	v_mul_f32_e32 v181, v159, v181
	v_mul_f32_e32 v182, v160, v182
	v_mul_f32_e32 v183, v161, v183
	v_mul_f32_e32 v184, v162, v184
	v_mul_f32_e32 v185, v163, v185
	v_readlane_b32 s24, v255, 9
	v_readlane_b32 s25, v255, 10
	s_lshl_b64 s[22:23], s[80:81], 11
	s_add_u32 s24, s24, s22
	s_addc_u32 s25, s25, s23
	v_mul_f32_e32 v2, v2, v202
	v_mul_f32_e32 v3, v3, v202
	v_mul_f32_e32 v4, v4, v202
	v_mul_f32_e32 v5, v5, v202
	v_mul_f32_e32 v6, v6, v202
	v_mul_f32_e32 v7, v7, v202
	v_mul_f32_e32 v8, v8, v202
	v_mul_f32_e32 v9, v9, v202
	v_mul_f32_e32 v10, v10, v202
	v_mul_f32_e32 v11, v11, v202
	v_mul_f32_e32 v12, v12, v202
	v_mul_f32_e32 v13, v13, v202
	v_mul_f32_e32 v14, v14, v202
	v_mul_f32_e32 v15, v15, v202
	v_mul_f32_e32 v16, v16, v202
	v_mul_f32_e32 v17, v17, v202
	v_fma_f32 v2, v2, v170, v186
	v_fma_f32 v3, v3, v171, v187
	v_fma_f32 v4, v4, v172, v188
	v_fma_f32 v5, v5, v173, v189
	v_fma_f32 v6, v6, v174, v190
	v_fma_f32 v7, v7, v175, v191
	v_fma_f32 v8, v8, v176, v192
	v_fma_f32 v9, v9, v177, v193
	v_fma_f32 v10, v10, v178, v194
	v_fma_f32 v11, v11, v179, v195
	v_fma_f32 v12, v12, v180, v196
	v_fma_f32 v13, v13, v181, v197
	v_fma_f32 v14, v14, v182, v198
	v_fma_f32 v15, v15, v183, v199
	v_fma_f32 v16, v16, v184, v200
	v_fma_f32 v17, v17, v185, v201
	v_cvt_pk_bf16_f32 v2, v2, v3
	v_cvt_pk_bf16_f32 v3, v4, v5
	v_cvt_pk_bf16_f32 v4, v6, v7
	v_cvt_pk_bf16_f32 v5, v8, v9
	v_cvt_pk_bf16_f32 v10, v10, v11
	v_cvt_pk_bf16_f32 v11, v12, v13
	v_cvt_pk_bf16_f32 v12, v14, v15
	v_cvt_pk_bf16_f32 v13, v16, v17
	global_store_dwordx4 v83, v[2:5], s[24:25]
	global_store_dwordx4 v83, v[10:13], s[24:25] offset:1024
	s_add_u32 s24, s24, 0x800
	s_addc_u32 s25, s25, 0
	v_mul_f32_e32 v18, v18, v203
	v_mul_f32_e32 v19, v19, v203
	v_mul_f32_e32 v20, v20, v203
	v_mul_f32_e32 v21, v21, v203
	v_mul_f32_e32 v22, v22, v203
	v_mul_f32_e32 v23, v23, v203
	v_mul_f32_e32 v24, v24, v203
	v_mul_f32_e32 v25, v25, v203
	v_mul_f32_e32 v26, v26, v203
	v_mul_f32_e32 v27, v27, v203
	v_mul_f32_e32 v28, v28, v203
	v_mul_f32_e32 v29, v29, v203
	v_mul_f32_e32 v30, v30, v203
	v_mul_f32_e32 v31, v31, v203
	v_mul_f32_e32 v32, v32, v203
	v_mul_f32_e32 v33, v33, v203
	v_fma_f32 v18, v18, v170, v186
	v_fma_f32 v19, v19, v171, v187
	v_fma_f32 v20, v20, v172, v188
	v_fma_f32 v21, v21, v173, v189
	v_fma_f32 v22, v22, v174, v190
	v_fma_f32 v23, v23, v175, v191
	v_fma_f32 v24, v24, v176, v192
	v_fma_f32 v25, v25, v177, v193
	v_fma_f32 v26, v26, v178, v194
	v_fma_f32 v27, v27, v179, v195
	v_fma_f32 v28, v28, v180, v196
	v_fma_f32 v29, v29, v181, v197
	v_fma_f32 v30, v30, v182, v198
	v_fma_f32 v31, v31, v183, v199
	v_fma_f32 v32, v32, v184, v200
	v_fma_f32 v33, v33, v185, v201
	v_cvt_pk_bf16_f32 v18, v18, v19
	v_cvt_pk_bf16_f32 v19, v20, v21
	v_cvt_pk_bf16_f32 v20, v22, v23
	v_cvt_pk_bf16_f32 v21, v24, v25
	v_cvt_pk_bf16_f32 v26, v26, v27
	v_cvt_pk_bf16_f32 v27, v28, v29
	v_cvt_pk_bf16_f32 v28, v30, v31
	v_cvt_pk_bf16_f32 v29, v32, v33
	global_store_dwordx4 v83, v[18:21], s[24:25]
	global_store_dwordx4 v83, v[26:29], s[24:25] offset:1024
	s_add_u32 s24, s24, 0x800
	s_addc_u32 s25, s25, 0
	v_mul_f32_e32 v34, v34, v204
	v_mul_f32_e32 v35, v35, v204
	v_mul_f32_e32 v36, v36, v204
	v_mul_f32_e32 v37, v37, v204
	v_mul_f32_e32 v38, v38, v204
	v_mul_f32_e32 v39, v39, v204
	v_mul_f32_e32 v40, v40, v204
	v_mul_f32_e32 v41, v41, v204
	v_mul_f32_e32 v42, v42, v204
	v_mul_f32_e32 v43, v43, v204
	v_mul_f32_e32 v44, v44, v204
	v_mul_f32_e32 v45, v45, v204
	v_mul_f32_e32 v46, v46, v204
	v_mul_f32_e32 v47, v47, v204
	v_mul_f32_e32 v48, v48, v204
	v_mul_f32_e32 v49, v49, v204
	v_fma_f32 v34, v34, v170, v186
	v_fma_f32 v35, v35, v171, v187
	v_fma_f32 v36, v36, v172, v188
	v_fma_f32 v37, v37, v173, v189
	v_fma_f32 v38, v38, v174, v190
	v_fma_f32 v39, v39, v175, v191
	v_fma_f32 v40, v40, v176, v192
	v_fma_f32 v41, v41, v177, v193
	v_fma_f32 v42, v42, v178, v194
	v_fma_f32 v43, v43, v179, v195
	v_fma_f32 v44, v44, v180, v196
	v_fma_f32 v45, v45, v181, v197
	v_fma_f32 v46, v46, v182, v198
	v_fma_f32 v47, v47, v183, v199
	v_fma_f32 v48, v48, v184, v200
	v_fma_f32 v49, v49, v185, v201
	v_cvt_pk_bf16_f32 v34, v34, v35
	v_cvt_pk_bf16_f32 v35, v36, v37
	v_cvt_pk_bf16_f32 v36, v38, v39
	v_cvt_pk_bf16_f32 v37, v40, v41
	v_cvt_pk_bf16_f32 v42, v42, v43
	v_cvt_pk_bf16_f32 v43, v44, v45
	v_cvt_pk_bf16_f32 v44, v46, v47
	v_cvt_pk_bf16_f32 v45, v48, v49
	global_store_dwordx4 v83, v[34:37], s[24:25]
	global_store_dwordx4 v83, v[42:45], s[24:25] offset:1024
	s_add_u32 s24, s24, 0x800
	s_addc_u32 s25, s25, 0
	v_mul_f32_e32 v50, v50, v205
	v_mul_f32_e32 v51, v51, v205
	v_mul_f32_e32 v52, v52, v205
	v_mul_f32_e32 v53, v53, v205
	v_mul_f32_e32 v54, v54, v205
	v_mul_f32_e32 v55, v55, v205
	v_mul_f32_e32 v56, v56, v205
	v_mul_f32_e32 v57, v57, v205
	v_mul_f32_e32 v58, v58, v205
	v_mul_f32_e32 v59, v59, v205
	v_mul_f32_e32 v60, v60, v205
	v_mul_f32_e32 v61, v61, v205
	v_mul_f32_e32 v62, v62, v205
	v_mul_f32_e32 v63, v63, v205
	v_mul_f32_e32 v64, v64, v205
	v_mul_f32_e32 v65, v65, v205
	v_fma_f32 v50, v50, v170, v186
	v_fma_f32 v51, v51, v171, v187
	v_fma_f32 v52, v52, v172, v188
	v_fma_f32 v53, v53, v173, v189
	v_fma_f32 v54, v54, v174, v190
	v_fma_f32 v55, v55, v175, v191
	v_fma_f32 v56, v56, v176, v192
	v_fma_f32 v57, v57, v177, v193
	v_fma_f32 v58, v58, v178, v194
	v_fma_f32 v59, v59, v179, v195
	v_fma_f32 v60, v60, v180, v196
	v_fma_f32 v61, v61, v181, v197
	v_fma_f32 v62, v62, v182, v198
	v_fma_f32 v63, v63, v183, v199
	v_fma_f32 v64, v64, v184, v200
	v_fma_f32 v65, v65, v185, v201
	v_cvt_pk_bf16_f32 v50, v50, v51
	v_cvt_pk_bf16_f32 v51, v52, v53
	v_cvt_pk_bf16_f32 v52, v54, v55
	v_cvt_pk_bf16_f32 v53, v56, v57
	v_cvt_pk_bf16_f32 v58, v58, v59
	v_cvt_pk_bf16_f32 v59, v60, v61
	v_cvt_pk_bf16_f32 v60, v62, v63
	v_cvt_pk_bf16_f32 v61, v64, v65
	global_store_dwordx4 v83, v[50:53], s[24:25]
	global_store_dwordx4 v83, v[58:61], s[24:25] offset:1024
	s_add_u32 s24, s24, 0x800
	s_addc_u32 s25, s25, 0
	v_mul_f32_e32 v66, v66, v206
	v_mul_f32_e32 v67, v67, v206
	v_mul_f32_e32 v68, v68, v206
	v_mul_f32_e32 v69, v69, v206
	v_mul_f32_e32 v70, v70, v206
	v_mul_f32_e32 v71, v71, v206
	v_mul_f32_e32 v72, v72, v206
	v_mul_f32_e32 v73, v73, v206
	v_mul_f32_e32 v74, v74, v206
	v_mul_f32_e32 v75, v75, v206
	v_mul_f32_e32 v76, v76, v206
	v_mul_f32_e32 v77, v77, v206
	v_mul_f32_e32 v78, v78, v206
	v_mul_f32_e32 v79, v79, v206
	v_mul_f32_e32 v80, v80, v206
	v_mul_f32_e32 v81, v81, v206
	v_fma_f32 v66, v66, v170, v186
	v_fma_f32 v67, v67, v171, v187
	v_fma_f32 v68, v68, v172, v188
	v_fma_f32 v69, v69, v173, v189
	v_fma_f32 v70, v70, v174, v190
	v_fma_f32 v71, v71, v175, v191
	v_fma_f32 v72, v72, v176, v192
	v_fma_f32 v73, v73, v177, v193
	v_fma_f32 v74, v74, v178, v194
	v_fma_f32 v75, v75, v179, v195
	v_fma_f32 v76, v76, v180, v196
	v_fma_f32 v77, v77, v181, v197
	v_fma_f32 v78, v78, v182, v198
	v_fma_f32 v79, v79, v183, v199
	v_fma_f32 v80, v80, v184, v200
	v_fma_f32 v81, v81, v185, v201
	v_cvt_pk_bf16_f32 v66, v66, v67
	v_cvt_pk_bf16_f32 v67, v68, v69
	v_cvt_pk_bf16_f32 v68, v70, v71
	v_cvt_pk_bf16_f32 v69, v72, v73
	v_cvt_pk_bf16_f32 v74, v74, v75
	v_cvt_pk_bf16_f32 v75, v76, v77
	v_cvt_pk_bf16_f32 v76, v78, v79
	v_cvt_pk_bf16_f32 v77, v80, v81
	global_store_dwordx4 v83, v[66:69], s[24:25]
	global_store_dwordx4 v83, v[74:77], s[24:25] offset:1024
	s_add_u32 s24, s24, 0x800
	s_addc_u32 s25, s25, 0
	v_mul_f32_e32 v132, v132, v207
	v_mul_f32_e32 v133, v133, v207
	v_mul_f32_e32 v134, v134, v207
	v_mul_f32_e32 v135, v135, v207
	v_mul_f32_e32 v136, v136, v207
	v_mul_f32_e32 v137, v137, v207
	v_mul_f32_e32 v138, v138, v207
	v_mul_f32_e32 v139, v139, v207
	v_mul_f32_e32 v140, v140, v207
	v_mul_f32_e32 v141, v141, v207
	v_mul_f32_e32 v142, v142, v207
	v_mul_f32_e32 v143, v143, v207
	v_mul_f32_e32 v144, v144, v207
	v_mul_f32_e32 v145, v145, v207
	v_mul_f32_e32 v146, v146, v207
	v_mul_f32_e32 v147, v147, v207
	v_fma_f32 v132, v132, v170, v186
	v_fma_f32 v133, v133, v171, v187
	v_fma_f32 v134, v134, v172, v188
	v_fma_f32 v135, v135, v173, v189
	v_fma_f32 v136, v136, v174, v190
	v_fma_f32 v137, v137, v175, v191
	v_fma_f32 v138, v138, v176, v192
	v_fma_f32 v139, v139, v177, v193
	v_fma_f32 v140, v140, v178, v194
	v_fma_f32 v141, v141, v179, v195
	v_fma_f32 v142, v142, v180, v196
	v_fma_f32 v143, v143, v181, v197
	v_fma_f32 v144, v144, v182, v198
	v_fma_f32 v145, v145, v183, v199
	v_fma_f32 v146, v146, v184, v200
	v_fma_f32 v147, v147, v185, v201
	v_cvt_pk_bf16_f32 v132, v132, v133
	v_cvt_pk_bf16_f32 v133, v134, v135
	v_cvt_pk_bf16_f32 v134, v136, v137
	v_cvt_pk_bf16_f32 v135, v138, v139
	v_cvt_pk_bf16_f32 v140, v140, v141
	v_cvt_pk_bf16_f32 v141, v142, v143
	v_cvt_pk_bf16_f32 v142, v144, v145
	v_cvt_pk_bf16_f32 v143, v146, v147
	global_store_dwordx4 v83, v[132:135], s[24:25]
	global_store_dwordx4 v83, v[140:143], s[24:25] offset:1024
	s_branch .LBB0_1012

	.amdhsa_kernel _Z14fwd_megakernel6Params
		.amdhsa_group_segment_fixed_size 0
		.amdhsa_private_segment_fixed_size 0
		.amdhsa_kernarg_size 536
		.amdhsa_user_sgpr_count 2
		.amdhsa_user_sgpr_dispatch_ptr 0
		.amdhsa_user_sgpr_queue_ptr 0
		.amdhsa_user_sgpr_kernarg_segment_ptr 1
		.amdhsa_user_sgpr_dispatch_id 0
		.amdhsa_user_sgpr_kernarg_preload_length 0
		.amdhsa_user_sgpr_kernarg_preload_offset 0
		.amdhsa_user_sgpr_private_segment_size 0
		.amdhsa_uses_dynamic_stack 0
		.amdhsa_enable_private_segment 0
		.amdhsa_system_sgpr_workgroup_id_x 1
		.amdhsa_system_sgpr_workgroup_id_y 0
		.amdhsa_system_sgpr_workgroup_id_z 0
		.amdhsa_system_sgpr_workgroup_info 0
		.amdhsa_system_vgpr_workitem_id 2
		.amdhsa_next_free_vgpr 256
		.amdhsa_next_free_sgpr 102
		.amdhsa_accum_offset 256
		.amdhsa_reserve_vcc 1
		.amdhsa_float_round_mode_32 0
		.amdhsa_float_round_mode_16_64 0
		.amdhsa_float_denorm_mode_32 3
		.amdhsa_float_denorm_mode_16_64 3
		.amdhsa_dx10_clamp 1
		.amdhsa_ieee_mode 1
		.amdhsa_fp16_overflow 0
		.amdhsa_tg_split 0
		.amdhsa_exception_fp_ieee_invalid_op 0
		.amdhsa_exception_fp_denorm_src 0
		.amdhsa_exception_fp_ieee_div_zero 0
		.amdhsa_exception_fp_ieee_overflow 0
		.amdhsa_exception_fp_ieee_underflow 0
		.amdhsa_exception_fp_ieee_inexact 0
		.amdhsa_exception_int_div_zero 0
	.end_amdhsa_kernel

amdhsa.kernels:
  - .agpr_count:     0
    .args:
      - .offset:         0
        .size:           280
        .value_kind:     by_value
      - .offset:         280
        .size:           4
        .value_kind:     hidden_block_count_x
      - .offset:         284
        .size:           4
        .value_kind:     hidden_block_count_y
      - .offset:         288
        .size:           4
        .value_kind:     hidden_block_count_z
      - .offset:         292
        .size:           2
        .value_kind:     hidden_group_size_x
      - .offset:         294
        .size:           2
        .value_kind:     hidden_group_size_y
      - .offset:         296
        .size:           2
        .value_kind:     hidden_group_size_z
      - .offset:         298
        .size:           2
        .value_kind:     hidden_remainder_x
      - .offset:         300
        .size:           2
        .value_kind:     hidden_remainder_y
      - .offset:         302
        .size:           2
        .value_kind:     hidden_remainder_z
      - .offset:         320
        .size:           8
        .value_kind:     hidden_global_offset_x
      - .offset:         328
        .size:           8
        .value_kind:     hidden_global_offset_y
      - .offset:         336
        .size:           8
        .value_kind:     hidden_global_offset_z
      - .offset:         344
        .size:           2
        .value_kind:     hidden_grid_dims
      - .offset:         368
        .size:           8
        .value_kind:     hidden_multigrid_sync_arg
      - .offset:         400
        .size:           4
        .value_kind:     hidden_dynamic_lds_size
    .group_segment_fixed_size: 0
    .kernarg_segment_align: 8
    .kernarg_segment_size: 536
    .language:       OpenCL C
    .language_version:
      - 2
      - 0
    .max_flat_workgroup_size: 512
    .name:           _Z14fwd_megakernel6Params
    .private_segment_fixed_size: 0
    .sgpr_count:     108
    .sgpr_spill_count: 234
    .symbol:         _Z14fwd_megakernel6Params.kd
    .uniform_work_group_size: 1
    .uses_dynamic_stack: false
    .vgpr_count:     256
    .vgpr_spill_count: 0
    .wavefront_size: 64
